# LN1 row loop: gamma/beta loads hoisted out of the row loop, next row prefetched into a register double buffer (one exposed round trip per wave instead of 3-4 per row)
# speedup vs baseline: 1.0054x; 1.0054x over previous
; DEV int opaque_tid() { int t = (int)threadIdx.x; asm volatile("" : "+v"(t)); return t; }
; DEV float lo_f(unsigned w) { return __uint_as_float(w << 16); }
; DEV float hi_f(unsigned w) { return __uint_as_float(w & 0xFFFF0000u); }
; __device__ void ln1_phase(const Params& P, int l) {
;   const int lane = opaque_tid() & 63, w = opaque_tid() >> 6;
;   for (int r4 = blockIdx.x; r4 < T_TOK / 4; r4 += gridDim.x) {
;     const int t = r4 * 4 + w;
;     const bf16_t* mx = P.MIX + (size_t)t * 1024;
;     bf16_t* xb = P.XB + (size_t)t * 1024;
;     float pre[16];
; #pragma unroll
;     for (int hsel = 0; hsel < 2; ++hsel) {
;       float r[8];
;       if (l == 0) {
;         const float* xr = P.x + (size_t)t * 1024 + hsel * 512 + lane * 8;
;         const float4 a = *(const float4*)xr, b = *(const float4*)(xr + 4);
;         r[0] = a.x; r[1] = a.y; r[2] = a.z; r[3] = a.w; r[4] = b.x; r[5] = b.y; r[6] = b.z; r[7] = b.w;
;       } else {
;         const uint4 xx = *(const uint4*)(xb + hsel * 512 + lane * 8);
;         r[0] = lo_f(xx.x); r[1] = hi_f(xx.x); r[2] = lo_f(xx.y); r[3] = hi_f(xx.y); r[4] = lo_f(xx.z); r[5] = hi_f(xx.z); r[6] = lo_f(xx.w); r[7] = hi_f(xx.w);
;       }
;       const uint4 mm = *(const uint4*)(mx + hsel * 512 + lane * 8);
;       pre[hsel * 8 + 0] = ALPHA_C * r[0] + lo_f(mm.x); pre[hsel * 8 + 1] = ALPHA_C * r[1] + hi_f(mm.x);
;       pre[hsel * 8 + 2] = ALPHA_C * r[2] + lo_f(mm.y); pre[hsel * 8 + 3] = ALPHA_C * r[3] + hi_f(mm.y);
;       pre[hsel * 8 + 4] = ALPHA_C * r[4] + lo_f(mm.z); pre[hsel * 8 + 5] = ALPHA_C * r[5] + hi_f(mm.z);
;       pre[hsel * 8 + 6] = ALPHA_C * r[6] + lo_f(mm.w); pre[hsel * 8 + 7] = ALPHA_C * r[7] + hi_f(mm.w);
;     }
.LBB0_56:
	global_load_dwordx4 v[64:67], v[24:25], off
	global_load_dwordx4 v[68:71], v[24:25], off offset:16
	global_load_dwordx4 v[72:75], v[26:27], off offset:16
	global_load_dwordx4 v[76:79], v[26:27], off
	global_load_dwordx4 v[80:83], v[26:27], off offset:2048
	global_load_dwordx4 v[84:87], v[24:25], off offset:2048
	global_load_dwordx4 v[88:91], v[24:25], off offset:2064
	global_load_dwordx4 v[92:95], v[26:27], off offset:2064
	v_ashrrev_i32_e32 v31, 31, v30
	v_lshlrev_b64 v[122:123], 11, v[30:31]
	v_lshl_add_u64 v[120:121], v[28:29], 0, v[122:123]
	v_lshlrev_b64 v[122:123], 10, v[30:31]
	v_lshl_add_u64 v[122:123], v[122:123], 1, v[20:21]
	s_and_b64 vcc, exec, s[6:7]
	s_cbranch_vccz .Lln1_pf0_a
	global_load_dwordx4 v[96:99], v[120:121], off
	global_load_dwordx4 v[104:107], v[120:121], off offset:1024
	global_load_dwordx4 v[112:115], v[122:123], off
	global_load_dwordx4 v[116:119], v[122:123], off offset:1024
	s_branch .Lln1_pfd_a
.Lln1_pf0_a:
	v_lshlrev_b64 v[60:61], 12, v[30:31]
	v_lshl_add_u64 v[60:61], v[22:23], 0, v[60:61]
	global_load_dwordx4 v[96:99], v[60:61], off
	global_load_dwordx4 v[100:103], v[60:61], off offset:16
	global_load_dwordx4 v[104:107], v[60:61], off offset:2048
	global_load_dwordx4 v[108:111], v[60:61], off offset:2064
	global_load_dwordx4 v[112:115], v[122:123], off
	global_load_dwordx4 v[116:119], v[122:123], off offset:1024
.Lln1_pfd_a:
	s_waitcnt vmcnt(0)
	s_branch .Lln1_copy
.Lln1_top:
	s_waitcnt vmcnt(2)
.Lln1_copy:
	v_pk_mov_b32 v[32:33], v[120:121], v[120:121] op_sel:[0,1]
	s_and_b64 vcc, exec, s[6:7]
	s_cbranch_vccz .Lln1_cp0
	v_lshlrev_b32_e32 v0, 16, v96
	v_and_b32_e32 v1, 0xffff0000, v96
	v_lshlrev_b32_e32 v2, 16, v97
	v_and_b32_e32 v3, 0xffff0000, v97
	v_lshlrev_b32_e32 v4, 16, v98
	v_and_b32_e32 v5, 0xffff0000, v98
	v_lshlrev_b32_e32 v6, 16, v99
	v_and_b32_e32 v7, 0xffff0000, v99
	v_lshlrev_b32_e32 v8, 16, v104
	v_and_b32_e32 v9, 0xffff0000, v104
	v_lshlrev_b32_e32 v10, 16, v105
	v_and_b32_e32 v11, 0xffff0000, v105
	v_lshlrev_b32_e32 v12, 16, v106
	v_and_b32_e32 v13, 0xffff0000, v106
	v_lshlrev_b32_e32 v14, 16, v107
	v_and_b32_e32 v15, 0xffff0000, v107
	s_branch .Lln1_adv
.Lln1_cp0:
	v_pk_mov_b32 v[0:1], v[96:97], v[96:97] op_sel:[0,1]
	v_pk_mov_b32 v[2:3], v[98:99], v[98:99] op_sel:[0,1]
	v_pk_mov_b32 v[4:5], v[100:101], v[100:101] op_sel:[0,1]
	v_pk_mov_b32 v[6:7], v[102:103], v[102:103] op_sel:[0,1]
	v_pk_mov_b32 v[8:9], v[104:105], v[104:105] op_sel:[0,1]
	v_pk_mov_b32 v[10:11], v[106:107], v[106:107] op_sel:[0,1]
	v_pk_mov_b32 v[12:13], v[108:109], v[108:109] op_sel:[0,1]
	v_pk_mov_b32 v[14:15], v[110:111], v[110:111] op_sel:[0,1]
.Lln1_adv:
	v_pk_mov_b32 v[16:17], v[112:113], v[112:113] op_sel:[0,1]
	v_pk_mov_b32 v[18:19], v[114:115], v[114:115] op_sel:[0,1]
	v_pk_mov_b32 v[34:35], v[116:117], v[116:117] op_sel:[0,1]
	v_pk_mov_b32 v[36:37], v[118:119], v[118:119] op_sel:[0,1]
	v_readlane_b32 s0, v248, 34
	s_add_i32 s4, s4, s0
	v_add_u32_e32 v30, s2, v30
	s_cmpk_gt_i32 s4, 0x1fff
	s_cbranch_scc1 .Lln1_body
	v_ashrrev_i32_e32 v31, 31, v30
	v_lshlrev_b64 v[122:123], 11, v[30:31]
	v_lshl_add_u64 v[120:121], v[28:29], 0, v[122:123]
	v_lshlrev_b64 v[122:123], 10, v[30:31]
	v_lshl_add_u64 v[122:123], v[122:123], 1, v[20:21]
	s_and_b64 vcc, exec, s[6:7]
	s_cbranch_vccz .Lln1_pf0_b
	global_load_dwordx4 v[96:99], v[120:121], off
	global_load_dwordx4 v[104:107], v[120:121], off offset:1024
	global_load_dwordx4 v[112:115], v[122:123], off
	global_load_dwordx4 v[116:119], v[122:123], off offset:1024
	s_branch .Lln1_pfd_b

; DEV float lo_f(unsigned w) { return __uint_as_float(w << 16); }
; DEV float hi_f(unsigned w) { return __uint_as_float(w & 0xFFFF0000u); }
; DEV void ln_row(const float* g, const float* bta, bf16_t* xb, int lane, const float (&pre)[16]) {
;   float s = 0.f;
; #pragma unroll
;   for (int k = 0; k < 16; ++k) s += pre[k];
;   const float mean = wave_sum(s) * (1.f / 1024.f);
;   float v = 0.f;
; #pragma unroll
;   for (int k = 0; k < 16; ++k) { const float d = pre[k] - mean; v += d * d; }
;   const float rstd = rsqrtf(wave_sum(v) * (1.f / 1024.f) + EPS_C);
; #pragma unroll
;   for (int hsel = 0; hsel < 2; ++hsel) {
;     const int c0 = hsel * 512 + lane * 8;
;     const float4 ga = *(const float4*)(g + c0), gb = *(const float4*)(g + c0 + 4);
;     const float4 ba = *(const float4*)(bta + c0), bb = *(const float4*)(bta + c0 + 4);
;     float o[8];
;     o[0] = (pre[hsel * 8 + 0] - mean) * rstd * ga.x + ba.x; o[1] = (pre[hsel * 8 + 1] - mean) * rstd * ga.y + ba.y;
;     o[2] = (pre[hsel * 8 + 2] - mean) * rstd * ga.z + ba.z; o[3] = (pre[hsel * 8 + 3] - mean) * rstd * ga.w + ba.w;
;     o[4] = (pre[hsel * 8 + 4] - mean) * rstd * gb.x + bb.x; o[5] = (pre[hsel * 8 + 5] - mean) * rstd * gb.y + bb.y;
;     o[6] = (pre[hsel * 8 + 6] - mean) * rstd * gb.z + bb.z; o[7] = (pre[hsel * 8 + 7] - mean) * rstd * gb.w + bb.w;
;     *(bf16x8*)(xb + c0) = pack8(o);
;   }
; __device__ void ln1_phase(const Params& P, int l) {
;     ...
;       pre[hsel * 8 + 0] = ALPHA_C * r[0] + lo_f(mm.x); pre[hsel * 8 + 1] = ALPHA_C * r[1] + hi_f(mm.x);
;       pre[hsel * 8 + 2] = ALPHA_C * r[2] + lo_f(mm.y); pre[hsel * 8 + 3] = ALPHA_C * r[3] + hi_f(mm.y);
;       pre[hsel * 8 + 4] = ALPHA_C * r[4] + lo_f(mm.z); pre[hsel * 8 + 5] = ALPHA_C * r[5] + hi_f(mm.z);
;       pre[hsel * 8 + 6] = ALPHA_C * r[6] + lo_f(mm.w); pre[hsel * 8 + 7] = ALPHA_C * r[7] + hi_f(mm.w);
;     }
;     ln_row(P.ln1_g + l * 1024, P.ln1_b + l * 1024, xb, lane, pre);
.Lln1_pfd_b:
.Lln1_body:
	v_lshlrev_b32_e32 v50, 16, v16
	v_and_b32_e32 v51, 0xffff0000, v16
	v_lshlrev_b32_e32 v52, 16, v17
	v_and_b32_e32 v53, 0xffff0000, v17
	v_lshlrev_b32_e32 v54, 16, v18
	v_and_b32_e32 v55, 0xffff0000, v18
	v_lshlrev_b32_e32 v56, 16, v19
	v_and_b32_e32 v57, 0xffff0000, v19
	s_mov_b32 s0, 0x3fb504f3
	v_pk_fma_f32 v[0:1], v[0:1], s[0:1], v[50:51] op_sel_hi:[1,0,1]
	v_pk_fma_f32 v[2:3], v[2:3], s[0:1], v[52:53] op_sel_hi:[1,0,1]
	v_add_f32_e32 v50, 0, v0
	v_add_f32_e32 v50, v1, v50
	v_add_f32_e32 v50, v2, v50
	v_pk_fma_f32 v[4:5], v[4:5], s[0:1], v[54:55] op_sel_hi:[1,0,1]
	v_add_f32_e32 v50, v3, v50
	v_add_f32_e32 v50, v4, v50
	v_pk_fma_f32 v[6:7], v[6:7], s[0:1], v[56:57] op_sel_hi:[1,0,1]
	v_add_f32_e32 v50, v5, v50
	v_add_f32_e32 v50, v6, v50
	v_add_f32_e32 v54, v7, v50
	v_mov_b32_e32 v31, v177
	v_mov_b32_e32 v58, v177
	v_mov_b32_e32 v62, v177
	v_mov_b32_e32 v63, v177
	v_lshlrev_b32_e32 v50, 16, v34
	v_and_b32_e32 v51, 0xffff0000, v34
	v_lshlrev_b32_e32 v34, 16, v35
	v_and_b32_e32 v35, 0xffff0000, v35
	v_pk_fma_f32 v[8:9], v[8:9], s[0:1], v[50:51] op_sel_hi:[1,0,1]
	v_pk_fma_f32 v[10:11], v[10:11], s[0:1], v[34:35] op_sel_hi:[1,0,1]
	v_add_f32_e32 v34, v54, v8
	v_add_f32_e32 v34, v9, v34
	v_lshlrev_b32_e32 v52, 16, v36
	v_and_b32_e32 v53, 0xffff0000, v36
	v_add_f32_e32 v34, v10, v34
	v_pk_fma_f32 v[12:13], v[12:13], s[0:1], v[52:53] op_sel_hi:[1,0,1]
	v_add_f32_e32 v34, v11, v34
	v_lshlrev_b32_e32 v36, 16, v37
	v_and_b32_e32 v37, 0xffff0000, v37
	v_add_f32_e32 v34, v12, v34
	v_pk_fma_f32 v[14:15], v[14:15], s[0:1], v[36:37] op_sel_hi:[1,0,1]
	v_add_f32_e32 v34, v13, v34
	v_add_f32_e32 v34, v14, v34
	v_add_f32_e32 v34, v15, v34
	s_nop 1
	v_add_f32_dpp v34, v34, v34 row_shr:1 row_mask:0xf bank_mask:0xf bound_ctrl:1
	s_nop 1
	v_add_f32_dpp v34, v34, v34 row_shr:2 row_mask:0xf bank_mask:0xf bound_ctrl:1
	s_nop 1
	v_add_f32_dpp v34, v34, v34 row_shr:4 row_mask:0xf bank_mask:0xf bound_ctrl:1
	s_nop 1
	v_add_f32_dpp v34, v34, v34 row_shr:8 row_mask:0xf bank_mask:0xf bound_ctrl:1
	s_nop 1
	v_mov_b32_dpp v31, v34 row_bcast:15 row_mask:0xa bank_mask:0xf
	v_add_f32_e32 v31, v34, v31
	s_nop 1
	v_mov_b32_dpp v58, v31 row_bcast:31 row_mask:0xc bank_mask:0xf
	v_add_f32_e32 v31, v31, v58
	s_nop 0
	v_readlane_b32 s0, v31, 63
	s_nop 1
	v_mul_f32_e32 v34, s0, v210
	v_pk_add_f32 v[0:1], v[0:1], v[34:35] op_sel_hi:[1,0] neg_lo:[0,1] neg_hi:[0,1]
	v_pk_add_f32 v[2:3], v[2:3], v[34:35] op_sel_hi:[1,0] neg_lo:[0,1] neg_hi:[0,1]
	v_pk_mul_f32 v[56:57], v[0:1], v[0:1]
	v_pk_mul_f32 v[54:55], v[2:3], v[2:3]
	v_add_f32_e32 v31, v56, v57
	v_pk_add_f32 v[4:5], v[4:5], v[34:35] op_sel_hi:[1,0] neg_lo:[0,1] neg_hi:[0,1]
	v_add_f32_e32 v31, v54, v31
	v_pk_add_f32 v[52:53], v[14:15], v[34:35] op_sel_hi:[1,0] neg_lo:[0,1] neg_hi:[0,1]
	v_pk_mul_f32 v[14:15], v[4:5], v[4:5]
	v_add_f32_e32 v31, v55, v31
	v_pk_add_f32 v[6:7], v[6:7], v[34:35] op_sel_hi:[1,0] neg_lo:[0,1] neg_hi:[0,1]
	v_add_f32_e32 v14, v14, v31
	v_pk_add_f32 v[36:37], v[8:9], v[34:35] op_sel_hi:[1,0] neg_lo:[0,1] neg_hi:[0,1]
	v_pk_add_f32 v[50:51], v[10:11], v[34:35] op_sel_hi:[1,0] neg_lo:[0,1] neg_hi:[0,1]
	v_pk_add_f32 v[34:35], v[12:13], v[34:35] op_sel_hi:[1,0] neg_lo:[0,1] neg_hi:[0,1]
	v_pk_mul_f32 v[12:13], v[6:7], v[6:7]
	v_add_f32_e32 v14, v15, v14
	v_add_f32_e32 v12, v12, v14
	v_pk_mul_f32 v[8:9], v[36:37], v[36:37]
	v_add_f32_e32 v12, v13, v12
	v_add_f32_e32 v8, v8, v12
	v_pk_mul_f32 v[10:11], v[50:51], v[50:51]
	v_add_f32_e32 v8, v9, v8
	v_add_f32_e32 v8, v10, v8
	v_pk_mul_f32 v[60:61], v[34:35], v[34:35]
	v_add_f32_e32 v8, v11, v8
	v_add_f32_e32 v8, v60, v8
	v_pk_mul_f32 v[58:59], v[52:53], v[52:53]
	v_add_f32_e32 v8, v61, v8
	v_add_f32_e32 v8, v58, v8
	v_add_f32_e32 v8, v59, v8
	s_nop 1
	v_add_f32_dpp v8, v8, v8 row_shr:1 row_mask:0xf bank_mask:0xf bound_ctrl:1
	s_nop 1
	v_add_f32_dpp v8, v8, v8 row_shr:2 row_mask:0xf bank_mask:0xf bound_ctrl:1
	s_nop 1
	v_add_f32_dpp v8, v8, v8 row_shr:4 row_mask:0xf bank_mask:0xf bound_ctrl:1
	s_nop 1
	v_add_f32_dpp v8, v8, v8 row_shr:8 row_mask:0xf bank_mask:0xf bound_ctrl:1
	s_nop 1
	v_mov_b32_dpp v62, v8 row_bcast:15 row_mask:0xa bank_mask:0xf
	v_add_f32_e32 v8, v8, v62
	s_nop 1
	v_mov_b32_dpp v63, v8 row_bcast:31 row_mask:0xc bank_mask:0xf
	v_add_f32_e32 v8, v8, v63
	s_nop 0
	v_readlane_b32 s0, v8, 63
	s_nop 1
	v_fma_f32 v8, s0, v210, v203
	s_mov_b32 s0, 0x800000
	v_mul_f32_e32 v9, 0x4b800000, v8
	v_cmp_gt_f32_e32 vcc, s0, v8
	v_cndmask_b32_e32 v8, v8, v9, vcc
	v_rsq_f32_e32 v8, v8
	v_readlane_b32 s1, v248, 35
	v_mul_f32_e32 v9, 0x45800000, v8
	v_cndmask_b32_e32 v54, v8, v9, vcc
	v_pk_mul_f32 v[0:1], v[0:1], v[54:55] op_sel_hi:[1,0]
	v_pk_mul_f32 v[2:3], v[2:3], v[54:55] op_sel_hi:[1,0]
	v_pk_mul_f32 v[4:5], v[4:5], v[54:55] op_sel_hi:[1,0]
	v_pk_mul_f32 v[6:7], v[6:7], v[54:55] op_sel_hi:[1,0]
	v_pk_fma_f32 v[0:1], v[64:65], v[0:1], v[76:77]
	v_pk_fma_f32 v[2:3], v[66:67], v[2:3], v[78:79]
	v_pk_fma_f32 v[4:5], v[68:69], v[4:5], v[72:73]
	v_pk_fma_f32 v[6:7], v[70:71], v[6:7], v[74:75]
	v_cvt_pk_bf16_f32 v0, v0, v1
	v_cvt_pk_bf16_f32 v1, v2, v3
	v_cvt_pk_bf16_f32 v2, v4, v5
	v_cvt_pk_bf16_f32 v3, v6, v7
	global_store_dwordx4 v[32:33], v[0:3], off
	s_nop 0
	v_pk_mul_f32 v[16:17], v[36:37], v[54:55] op_sel_hi:[1,0]
	v_pk_mul_f32 v[18:19], v[50:51], v[54:55] op_sel_hi:[1,0]
	v_pk_mul_f32 v[34:35], v[34:35], v[54:55] op_sel_hi:[1,0]
	v_pk_mul_f32 v[36:37], v[52:53], v[54:55] op_sel_hi:[1,0]
	v_pk_fma_f32 v[0:1], v[16:17], v[84:85], v[80:81]
	v_pk_fma_f32 v[2:3], v[18:19], v[86:87], v[82:83]
	v_pk_fma_f32 v[4:5], v[34:35], v[88:89], v[92:93]
	v_pk_fma_f32 v[6:7], v[36:37], v[90:91], v[94:95]
	v_cvt_pk_bf16_f32 v0, v0, v1
	v_cvt_pk_bf16_f32 v1, v2, v3
	v_cvt_pk_bf16_f32 v2, v4, v5
	v_cvt_pk_bf16_f32 v3, v6, v7
	global_store_dwordx4 v[32:33], v[0:3], off offset:1024
	s_cmpk_gt_i32 s4, 0x1fff
	s_cbranch_scc0 .Lln1_top
